# gated GEMM B epilogue too: gate + read-back loads run 4 row blocks ahead with counted vmcnt (was 2 loads + vmcnt(0) per block)
# speedup vs baseline: 1.0229x; 1.0091x over previous
; #define PG8_STAGE(bufoff, gbase, voff) do { _Pragma("unroll") for (int _i = 0; _i < 2; ++_i) \
;         __builtin_amdgcn_global_load_lds((const unsigned*)((const char*)(gbase) + (voff)[_i]), (PG8_LAS unsigned*)(lds + (bufoff) + ldsw + _i * 8192), 16, 0, 0); } while (0)
; #define PG8_LDA(dst, b, h) do { _Pragma("unroll") for (int m = 0; m < 4; ++m) _Pragma("unroll") for (int k = 0; k < 2; ++k) dst[m][k] = *(const PG8_LAS bf16x8*)(lds + PG8_SA(b, h) + aoff + m * 2048 + k * 1024); } while (0)
; #define PG8_LDB(dst, b, h) do { _Pragma("unroll") for (int n = 0; n < 2; ++n) _Pragma("unroll") for (int k = 0; k < 2; ++k) dst[n][k] = *(const PG8_LAS bf16x8*)(lds + PG8_SB(b, h) + boff + n * 2048 + k * 1024); } while (0)
; #define PG8_MMA(ai, bj, At, Bt) do { __builtin_amdgcn_s_setprio(1); _Pragma("unroll") for (int m = 0; m < 4; ++m) _Pragma("unroll") for (int n = 0; n < 2; ++n) _Pragma("unroll") for (int k = 0; k < 2; ++k) \
;         acc[ai][bj][m][n] = __builtin_amdgcn_mfma_f32_16x16x32_bf16(Bt[n][k], At[m][k], acc[ai][bj][m][n], 0, 0, 0); __builtin_amdgcn_s_setprio(0); } while (0)
; #define PG8_WAIT_V(n) asm volatile("s_waitcnt vmcnt(" #n ")" ::: "memory")
; #define PG8_WAIT_L(n) asm volatile("s_waitcnt lgkmcnt(" #n ")" ::: "memory")
; #define PG8_BAR __builtin_amdgcn_s_barrier()
; #define PG8_SCHED __builtin_amdgcn_sched_barrier(0)
; template <class Epi, class Sched>
; __device__ __forceinline__ void gemm_phase(PG8_LAS unsigned char* lds, const Gemm g, const Sched& S, const Epi& E) {
;     ...
;             PG8_LDB(B0, 0, 0); PG8_SCHED; PG8_LDA(At, 0, 0); PG8_STAGE(PG8_SA(1, 1), a1 + hstep, voffA);
;             PG8_WAIT_L(8); PG8_BAR; PG8_WAIT_L(0); PG8_MMA(0, 0, At, B0); PG8_BAR; PG8_SCHED;
;             PG8_LDB(B1, 0, 1); PG8_STAGE(PG8_SB(0, 0), b2, voffB);
;             PG8_BAR; PG8_WAIT_L(0); PG8_MMA(0, 1, At, B1); PG8_BAR;
;             PG8_LDA(At, 0, 1); PG8_STAGE(PG8_SA(0, 0), a2, voffA);
;             PG8_BAR; PG8_WAIT_L(0); PG8_MMA(1, 0, At, B0); PG8_BAR; PG8_SCHED;
;             PG8_STAGE(PG8_SB(0, 1), b2 + hstep, voffB);
;             PG8_WAIT_V(6); PG8_BAR; PG8_MMA(1, 1, At, B1); PG8_BAR;
.LBB0_1011:
	ds_read_b128 v[144:147], v153
	ds_read_b128 v[156:159], v153 offset:1024
	ds_read_b128 v[160:163], v153 offset:2048
	ds_read_b128 v[164:167], v153 offset:3072
	s_add_u32 s20, s18, 0xfffc0080
	s_addc_u32 s21, s19, -1
	s_cmp_eq_u32 s47, 12
	s_cselect_b32 s23, s11, s21
	s_cselect_b32 s22, s43, s20
	s_cselect_b32 s21, s9, s46
	s_cselect_b32 s20, s44, s45
	s_add_i32 m0, s17, 0xc000
	ds_read_b128 v[168:171], v154
	ds_read_b128 v[172:175], v154 offset:1024
	ds_read_b128 v[182:185], v154 offset:2048
	ds_read_b128 v[190:193], v154 offset:3072
	ds_read_b128 v[194:197], v154 offset:4096
	ds_read_b128 v[198:201], v154 offset:5120
	ds_read_b128 v[202:205], v154 offset:6144
	ds_read_b128 v[206:209], v154 offset:7168
	global_load_lds_dwordx4 v136, s[18:19]
	s_nop 1
	s_add_i32 m0, s17, 0xe000
	s_nop 0
	global_load_lds_dwordx4 v138, s[18:19]
	s_waitcnt lgkmcnt(8)
	ds_read_b128 v[210:213], v155
	ds_read_b128 v[214:217], v155 offset:1024
	ds_read_b128 v[218:221], v155 offset:2048
	ds_read_b128 v[222:225], v155 offset:3072
	s_waitcnt vmcnt(8) lgkmcnt(0)
	s_barrier
	v_mfma_f32_16x16x32_bf16 v[124:127], v[144:147], v[168:171], v[124:127]
	v_mfma_f32_16x16x32_bf16 v[120:123], v[160:163], v[168:171], v[120:123]
	v_mfma_f32_16x16x32_bf16 v[108:111], v[144:147], v[182:185], v[108:111]
	v_mfma_f32_16x16x32_bf16 v[104:107], v[160:163], v[182:185], v[104:107]
	v_mfma_f32_16x16x32_bf16 v[92:95], v[144:147], v[194:197], v[92:95]
	v_mfma_f32_16x16x32_bf16 v[88:91], v[160:163], v[194:197], v[88:91]
	v_mfma_f32_16x16x32_bf16 v[76:79], v[144:147], v[202:205], v[76:79]
	v_mfma_f32_16x16x32_bf16 v[72:75], v[160:163], v[202:205], v[72:75]
	v_mfma_f32_16x16x32_bf16 v[124:127], v[156:159], v[172:175], v[124:127]
	v_mfma_f32_16x16x32_bf16 v[120:123], v[164:167], v[172:175], v[120:123]
	v_mfma_f32_16x16x32_bf16 v[108:111], v[156:159], v[190:193], v[108:111]
	v_mfma_f32_16x16x32_bf16 v[104:107], v[164:167], v[190:193], v[104:107]
	v_mfma_f32_16x16x32_bf16 v[92:95], v[156:159], v[198:201], v[92:95]
	v_mfma_f32_16x16x32_bf16 v[88:91], v[164:167], v[198:201], v[88:91]
	v_mfma_f32_16x16x32_bf16 v[76:79], v[156:159], v[206:209], v[76:79]
	v_mfma_f32_16x16x32_bf16 v[72:75], v[164:167], v[206:209], v[72:75]
	v_mfma_f32_16x16x32_bf16 v[116:119], v[210:213], v[168:171], v[116:119]
	v_mfma_f32_16x16x32_bf16 v[112:115], v[218:221], v[168:171], v[112:115]
	v_mfma_f32_16x16x32_bf16 v[100:103], v[210:213], v[182:185], v[100:103]
	v_mfma_f32_16x16x32_bf16 v[96:99], v[218:221], v[182:185], v[96:99]
	v_mfma_f32_16x16x32_bf16 v[84:87], v[210:213], v[194:197], v[84:87]
	v_mfma_f32_16x16x32_bf16 v[80:83], v[218:221], v[194:197], v[80:83]
	v_mfma_f32_16x16x32_bf16 v[68:71], v[210:213], v[202:205], v[68:71]
	v_mfma_f32_16x16x32_bf16 v[64:67], v[218:221], v[202:205], v[64:67]
	v_mfma_f32_16x16x32_bf16 v[116:119], v[214:217], v[172:175], v[116:119]
	v_mfma_f32_16x16x32_bf16 v[112:115], v[222:225], v[172:175], v[112:115]
	v_mfma_f32_16x16x32_bf16 v[100:103], v[214:217], v[190:193], v[100:103]
	v_mfma_f32_16x16x32_bf16 v[96:99], v[222:225], v[190:193], v[96:99]
	v_mfma_f32_16x16x32_bf16 v[84:87], v[214:217], v[198:201], v[84:87]
	v_mfma_f32_16x16x32_bf16 v[80:83], v[222:225], v[198:201], v[80:83]
	v_mfma_f32_16x16x32_bf16 v[68:71], v[214:217], v[206:209], v[68:71]
	v_mfma_f32_16x16x32_bf16 v[64:67], v[222:225], v[206:209], v[64:67]
	s_barrier
	ds_read_b128 v[168:171], v154 offset:16384
	ds_read_b128 v[172:175], v154 offset:17408
	ds_read_b128 v[182:185], v154 offset:18432
	ds_read_b128 v[190:193], v154 offset:19456
	ds_read_b128 v[194:197], v154 offset:20480
	ds_read_b128 v[198:201], v154 offset:21504
	ds_read_b128 v[202:205], v154 offset:22528
	ds_read_b128 v[206:209], v154 offset:23552
	s_add_i32 s48, s39, s29
	s_add_u32 s98, s20, s6
	s_addc_u32 s99, s21, s7
	s_mov_b32 m0, s48
	s_nop 0
	global_load_lds_dwordx4 v130, s[20:21]
	s_nop 1
	s_add_i32 m0, s48, 0x2000
	s_nop 0
	global_load_lds_dwordx4 v134, s[20:21]
	s_nop 1
	s_mov_b32 m0, s17
	s_add_u32 s100, s22, s6
	s_addc_u32 s101, s23, s7
	global_load_lds_dwordx4 v128, s[22:23]
	s_nop 1
	s_mov_b32 m0, s30
	s_nop 0
	global_load_lds_dwordx4 v132, s[22:23]
	s_add_u32 s48, s20, 0x40000
	s_addc_u32 s49, s21, 0
	s_add_i32 s50, s40, s29
	s_mov_b32 m0, s50
	s_nop 0
	global_load_lds_dwordx4 v130, s[48:49]
	s_nop 1
	s_add_i32 m0, s50, 0x2000
	s_nop 0
	global_load_lds_dwordx4 v134, s[48:49]
	s_waitcnt vmcnt(8) lgkmcnt(0)
	s_barrier
	v_mfma_f32_16x16x32_bf16 v[60:63], v[144:147], v[168:171], v[60:63]
	v_mfma_f32_16x16x32_bf16 v[56:59], v[160:163], v[168:171], v[56:59]
	v_mfma_f32_16x16x32_bf16 v[44:47], v[144:147], v[182:185], v[44:47]
	v_mfma_f32_16x16x32_bf16 v[40:43], v[160:163], v[182:185], v[40:43]
	v_mfma_f32_16x16x32_bf16 v[28:31], v[144:147], v[194:197], v[28:31]
	v_mfma_f32_16x16x32_bf16 v[24:27], v[160:163], v[194:197], v[24:27]
	v_mfma_f32_16x16x32_bf16 v[12:15], v[144:147], v[202:205], v[12:15]
	v_mfma_f32_16x16x32_bf16 v[8:11], v[160:163], v[202:205], v[8:11]
	v_mfma_f32_16x16x32_bf16 v[60:63], v[156:159], v[172:175], v[60:63]
	v_mfma_f32_16x16x32_bf16 v[56:59], v[164:167], v[172:175], v[56:59]
	v_mfma_f32_16x16x32_bf16 v[44:47], v[156:159], v[190:193], v[44:47]
	v_mfma_f32_16x16x32_bf16 v[40:43], v[164:167], v[190:193], v[40:43]
	v_mfma_f32_16x16x32_bf16 v[28:31], v[156:159], v[198:201], v[28:31]
	v_mfma_f32_16x16x32_bf16 v[24:27], v[164:167], v[198:201], v[24:27]
	v_mfma_f32_16x16x32_bf16 v[12:15], v[156:159], v[206:209], v[12:15]
	v_mfma_f32_16x16x32_bf16 v[8:11], v[164:167], v[206:209], v[8:11]
	v_mfma_f32_16x16x32_bf16 v[52:55], v[210:213], v[168:171], v[52:55]
	v_mfma_f32_16x16x32_bf16 v[48:51], v[218:221], v[168:171], v[48:51]
	v_mfma_f32_16x16x32_bf16 v[36:39], v[210:213], v[182:185], v[36:39]
	v_mfma_f32_16x16x32_bf16 v[32:35], v[218:221], v[182:185], v[32:35]
	v_mfma_f32_16x16x32_bf16 v[20:23], v[210:213], v[194:197], v[20:23]
	v_mfma_f32_16x16x32_bf16 v[16:19], v[218:221], v[194:197], v[16:19]
	v_mfma_f32_16x16x32_bf16 v[4:7], v[210:213], v[202:205], v[4:7]
	v_mfma_f32_16x16x32_bf16 v[0:3], v[218:221], v[202:205], v[0:3]
	v_mfma_f32_16x16x32_bf16 v[52:55], v[214:217], v[172:175], v[52:55]
	v_mfma_f32_16x16x32_bf16 v[48:51], v[222:225], v[172:175], v[48:51]
	v_mfma_f32_16x16x32_bf16 v[36:39], v[214:217], v[190:193], v[36:39]
	v_mfma_f32_16x16x32_bf16 v[32:35], v[222:225], v[190:193], v[32:35]
	v_mfma_f32_16x16x32_bf16 v[20:23], v[214:217], v[198:201], v[20:23]
	v_mfma_f32_16x16x32_bf16 v[16:19], v[222:225], v[198:201], v[16:19]
	v_mfma_f32_16x16x32_bf16 v[4:7], v[214:217], v[206:209], v[4:7]
	v_mfma_f32_16x16x32_bf16 v[0:3], v[222:225], v[206:209], v[0:3]
	s_barrier
; #define PG8_STAGE(bufoff, gbase, voff) do { _Pragma("unroll") for (int _i = 0; _i < 2; ++_i) \
;         __builtin_amdgcn_global_load_lds((const unsigned*)((const char*)(gbase) + (voff)[_i]), (PG8_LAS unsigned*)(lds + (bufoff) + ldsw + _i * 8192), 16, 0, 0); } while (0)
; #define PG8_LDA(dst, b, h) do { _Pragma("unroll") for (int m = 0; m < 4; ++m) _Pragma("unroll") for (int k = 0; k < 2; ++k) dst[m][k] = *(const PG8_LAS bf16x8*)(lds + PG8_SA(b, h) + aoff + m * 2048 + k * 1024); } while (0)
; #define PG8_LDB(dst, b, h) do { _Pragma("unroll") for (int n = 0; n < 2; ++n) _Pragma("unroll") for (int k = 0; k < 2; ++k) dst[n][k] = *(const PG8_LAS bf16x8*)(lds + PG8_SB(b, h) + boff + n * 2048 + k * 1024); } while (0)
; #define PG8_MMA(ai, bj, At, Bt) do { __builtin_amdgcn_s_setprio(1); _Pragma("unroll") for (int m = 0; m < 4; ++m) _Pragma("unroll") for (int n = 0; n < 2; ++n) _Pragma("unroll") for (int k = 0; k < 2; ++k) \
;         acc[ai][bj][m][n] = __builtin_amdgcn_mfma_f32_16x16x32_bf16(Bt[n][k], At[m][k], acc[ai][bj][m][n], 0, 0, 0); __builtin_amdgcn_s_setprio(0); } while (0)
; #define PG8_WAIT_V(n) asm volatile("s_waitcnt vmcnt(" #n ")" ::: "memory")
; #define PG8_WAIT_L(n) asm volatile("s_waitcnt lgkmcnt(" #n ")" ::: "memory")
; #define PG8_BAR __builtin_amdgcn_s_barrier()
; #define PG8_SCHED __builtin_amdgcn_sched_barrier(0)
; template <class Epi, class Sched>
; __device__ __forceinline__ void gemm_phase(PG8_LAS unsigned char* lds, const Gemm g, const Sched& S, const Epi& E) {
;     ...
;             PG8_LDB(B0, 1, 0); PG8_SCHED; PG8_LDA(At, 1, 0); PG8_STAGE(PG8_SA(0, 1), a2 + hstep, voffA);
;             PG8_WAIT_L(8); PG8_BAR; PG8_WAIT_L(0); PG8_MMA(0, 0, At, B0); PG8_BAR; PG8_SCHED;
;             PG8_LDB(B1, 1, 1); PG8_STAGE(PG8_SB(1, 0), b3, voffB);
;             PG8_BAR; PG8_WAIT_L(0); PG8_MMA(0, 1, At, B1); PG8_BAR;
;             PG8_LDA(At, 1, 1); PG8_STAGE(PG8_SA(1, 0), a3, voffA);
;             PG8_BAR; PG8_WAIT_L(0); PG8_MMA(1, 0, At, B0); PG8_BAR; PG8_SCHED;
;             PG8_STAGE(PG8_SB(1, 1), b3 + hstep, voffB);
;             PG8_WAIT_V(6); PG8_BAR; PG8_MMA(1, 1, At, B1); PG8_BAR;
	s_add_i32 s48, 0, 0x18000
	v_add_u32_e32 v164, s48, v151
	ds_read_b128 v[144:147], v164
	ds_read_b128 v[156:159], v164 offset:1024
	ds_read_b128 v[160:163], v164 offset:2048
	ds_read_b128 v[164:167], v164 offset:3072
	s_add_u32 s22, s22, 0x40000
	s_addc_u32 s23, s23, 0
	s_mov_b32 m0, s31
	ds_read_b128 v[168:171], v154 offset:32768
	ds_read_b128 v[172:175], v154 offset:33792
	ds_read_b128 v[182:185], v154 offset:34816
	ds_read_b128 v[190:193], v154 offset:35840
	ds_read_b128 v[194:197], v154 offset:36864
	ds_read_b128 v[198:201], v154 offset:37888
	ds_read_b128 v[202:205], v154 offset:38912
	ds_read_b128 v[206:209], v154 offset:39936
	global_load_lds_dwordx4 v128, s[22:23]
	s_nop 1
	s_mov_b32 m0, s34
	s_nop 0
	global_load_lds_dwordx4 v132, s[22:23]
	s_add_i32 s22, 0, 0x1c000
	v_add_u32_e32 v179, s22, v151
	s_waitcnt lgkmcnt(8)
	ds_read_b128 v[210:213], v179
	ds_read_b128 v[214:217], v179 offset:1024
	ds_read_b128 v[218:221], v179 offset:2048
	ds_read_b128 v[222:225], v179 offset:3072
	s_waitcnt vmcnt(8) lgkmcnt(0)
	s_barrier
	v_mfma_f32_16x16x32_bf16 v[124:127], v[144:147], v[168:171], v[124:127]
	v_mfma_f32_16x16x32_bf16 v[120:123], v[160:163], v[168:171], v[120:123]
	v_mfma_f32_16x16x32_bf16 v[108:111], v[144:147], v[182:185], v[108:111]
	v_mfma_f32_16x16x32_bf16 v[104:107], v[160:163], v[182:185], v[104:107]
	v_mfma_f32_16x16x32_bf16 v[92:95], v[144:147], v[194:197], v[92:95]
	v_mfma_f32_16x16x32_bf16 v[88:91], v[160:163], v[194:197], v[88:91]
	v_mfma_f32_16x16x32_bf16 v[76:79], v[144:147], v[202:205], v[76:79]
	v_mfma_f32_16x16x32_bf16 v[72:75], v[160:163], v[202:205], v[72:75]
	v_mfma_f32_16x16x32_bf16 v[124:127], v[156:159], v[172:175], v[124:127]
	v_mfma_f32_16x16x32_bf16 v[120:123], v[164:167], v[172:175], v[120:123]
	v_mfma_f32_16x16x32_bf16 v[108:111], v[156:159], v[190:193], v[108:111]
	v_mfma_f32_16x16x32_bf16 v[104:107], v[164:167], v[190:193], v[104:107]
	v_mfma_f32_16x16x32_bf16 v[92:95], v[156:159], v[198:201], v[92:95]
	v_mfma_f32_16x16x32_bf16 v[88:91], v[164:167], v[198:201], v[88:91]
	v_mfma_f32_16x16x32_bf16 v[76:79], v[156:159], v[206:209], v[76:79]
	v_mfma_f32_16x16x32_bf16 v[72:75], v[164:167], v[206:209], v[72:75]
	v_mfma_f32_16x16x32_bf16 v[116:119], v[210:213], v[168:171], v[116:119]
	v_mfma_f32_16x16x32_bf16 v[112:115], v[218:221], v[168:171], v[112:115]
	v_mfma_f32_16x16x32_bf16 v[100:103], v[210:213], v[182:185], v[100:103]
	v_mfma_f32_16x16x32_bf16 v[96:99], v[218:221], v[182:185], v[96:99]
	v_mfma_f32_16x16x32_bf16 v[84:87], v[210:213], v[194:197], v[84:87]
	v_mfma_f32_16x16x32_bf16 v[80:83], v[218:221], v[194:197], v[80:83]
	v_mfma_f32_16x16x32_bf16 v[68:71], v[210:213], v[202:205], v[68:71]
	v_mfma_f32_16x16x32_bf16 v[64:67], v[218:221], v[202:205], v[64:67]
	v_mfma_f32_16x16x32_bf16 v[116:119], v[214:217], v[172:175], v[116:119]
	v_mfma_f32_16x16x32_bf16 v[112:115], v[222:225], v[172:175], v[112:115]
	v_mfma_f32_16x16x32_bf16 v[100:103], v[214:217], v[190:193], v[100:103]
	v_mfma_f32_16x16x32_bf16 v[96:99], v[222:225], v[190:193], v[96:99]
	v_mfma_f32_16x16x32_bf16 v[84:87], v[214:217], v[198:201], v[84:87]
	v_mfma_f32_16x16x32_bf16 v[80:83], v[222:225], v[198:201], v[80:83]
	v_mfma_f32_16x16x32_bf16 v[68:71], v[214:217], v[206:209], v[68:71]
	v_mfma_f32_16x16x32_bf16 v[64:67], v[222:225], v[206:209], v[64:67]
	s_barrier
	ds_read_b128 v[168:171], v154 offset:49152
	ds_read_b128 v[172:175], v154 offset:50176
	ds_read_b128 v[182:185], v154 offset:51200
	ds_read_b128 v[190:193], v154 offset:52224
	ds_read_b128 v[194:197], v154 offset:53248
	ds_read_b128 v[198:201], v154 offset:54272
	ds_read_b128 v[202:205], v154 offset:55296
	ds_read_b128 v[206:209], v154 offset:56320
	s_add_i32 s23, s48, s29
	s_mov_b32 m0, s23
	s_nop 0
	global_load_lds_dwordx4 v130, s[98:99]
	s_nop 1
	s_add_i32 m0, s23, 0x2000
	s_nop 0
	global_load_lds_dwordx4 v134, s[98:99]
	s_nop 1
	s_mov_b32 m0, s36
	s_nop 0
	global_load_lds_dwordx4 v128, s[100:101]
	s_nop 1
	s_mov_b32 m0, s37
	s_nop 0
	global_load_lds_dwordx4 v132, s[100:101]
	s_add_u32 s20, s20, 0x40080
	s_addc_u32 s21, s21, 0
	s_add_i32 s22, s22, s29
	s_mov_b32 m0, s22
	s_nop 0
	global_load_lds_dwordx4 v130, s[20:21]
	s_nop 1
	s_add_i32 m0, s22, 0x2000
	s_nop 0
	global_load_lds_dwordx4 v134, s[20:21]
	s_waitcnt vmcnt(8) lgkmcnt(0)
	s_barrier
	v_mfma_f32_16x16x32_bf16 v[60:63], v[144:147], v[168:171], v[60:63]
	v_mfma_f32_16x16x32_bf16 v[56:59], v[160:163], v[168:171], v[56:59]
	v_mfma_f32_16x16x32_bf16 v[44:47], v[144:147], v[182:185], v[44:47]
	v_mfma_f32_16x16x32_bf16 v[40:43], v[160:163], v[182:185], v[40:43]
	v_mfma_f32_16x16x32_bf16 v[28:31], v[144:147], v[194:197], v[28:31]
	v_mfma_f32_16x16x32_bf16 v[24:27], v[160:163], v[194:197], v[24:27]
	v_mfma_f32_16x16x32_bf16 v[12:15], v[144:147], v[202:205], v[12:15]
	v_mfma_f32_16x16x32_bf16 v[8:11], v[160:163], v[202:205], v[8:11]
	v_mfma_f32_16x16x32_bf16 v[60:63], v[156:159], v[172:175], v[60:63]
	v_mfma_f32_16x16x32_bf16 v[56:59], v[164:167], v[172:175], v[56:59]
	v_mfma_f32_16x16x32_bf16 v[44:47], v[156:159], v[190:193], v[44:47]
	v_mfma_f32_16x16x32_bf16 v[40:43], v[164:167], v[190:193], v[40:43]
	v_mfma_f32_16x16x32_bf16 v[28:31], v[156:159], v[198:201], v[28:31]
	v_mfma_f32_16x16x32_bf16 v[24:27], v[164:167], v[198:201], v[24:27]
	v_mfma_f32_16x16x32_bf16 v[12:15], v[156:159], v[206:209], v[12:15]
	v_mfma_f32_16x16x32_bf16 v[8:11], v[164:167], v[206:209], v[8:11]
	v_mfma_f32_16x16x32_bf16 v[52:55], v[210:213], v[168:171], v[52:55]
	v_mfma_f32_16x16x32_bf16 v[48:51], v[218:221], v[168:171], v[48:51]
	v_mfma_f32_16x16x32_bf16 v[36:39], v[210:213], v[182:185], v[36:39]
	v_mfma_f32_16x16x32_bf16 v[32:35], v[218:221], v[182:185], v[32:35]
	v_mfma_f32_16x16x32_bf16 v[20:23], v[210:213], v[194:197], v[20:23]
	v_mfma_f32_16x16x32_bf16 v[16:19], v[218:221], v[194:197], v[16:19]
	v_mfma_f32_16x16x32_bf16 v[4:7], v[210:213], v[202:205], v[4:7]
	v_mfma_f32_16x16x32_bf16 v[0:3], v[218:221], v[202:205], v[0:3]
	v_mfma_f32_16x16x32_bf16 v[52:55], v[214:217], v[172:175], v[52:55]
	v_mfma_f32_16x16x32_bf16 v[48:51], v[222:225], v[172:175], v[48:51]
	v_mfma_f32_16x16x32_bf16 v[36:39], v[214:217], v[190:193], v[36:39]
	v_mfma_f32_16x16x32_bf16 v[32:35], v[222:225], v[190:193], v[32:35]
	v_mfma_f32_16x16x32_bf16 v[20:23], v[214:217], v[198:201], v[20:23]
	v_mfma_f32_16x16x32_bf16 v[16:19], v[222:225], v[198:201], v[16:19]
	v_mfma_f32_16x16x32_bf16 v[4:7], v[214:217], v[206:209], v[4:7]
	v_mfma_f32_16x16x32_bf16 v[0:3], v[222:225], v[206:209], v[0:3]
	s_barrier
; __device__ __forceinline__ unsigned cvt_pk_bf16(float lo, float hi) { unsigned r; asm volatile("v_cvt_pk_bf16_f32 %0, %1, %2" : "=v"(r) : "v"(lo), "v"(hi)); return r; }
; __device__ __forceinline__ float bf_lo(unsigned u) { return __uint_as_float(u << 16); }
; __device__ __forceinline__ float bf_hi(unsigned u) { return __uint_as_float(u & 0xffff0000u); }
; #define PG8_MMA(ai, bj, At, Bt) do { __builtin_amdgcn_s_setprio(1); _Pragma("unroll") for (int m = 0; m < 4; ++m) _Pragma("unroll") for (int n = 0; n < 2; ++n) _Pragma("unroll") for (int k = 0; k < 2; ++k) \
;         acc[ai][bj][m][n] = __builtin_amdgcn_mfma_f32_16x16x32_bf16(Bt[n][k], At[m][k], acc[ai][bj][m][n], 0, 0, 0); __builtin_amdgcn_s_setprio(0); } while (0)
; #define PG8_WAIT_V(n) asm volatile("s_waitcnt vmcnt(" #n ")" ::: "memory")
; #define PG8_BAR __builtin_amdgcn_s_barrier()
;     __device__ __forceinline__ void operator()(const f32x4 (&acc)[2][2][4][2], const Unit& u, int wr, int wc, int fr, int fq) const {
;     ...
;             for (int m = 0; m < 4; ++m) { const size_t r = (size_t)(row0 + ai * HALF + m * 16); bf16_t* rowp = O + r * ldc + col0; const bf16_t* gp = G + r * ldg + col0;
; #pragma unroll
;                 for (int bj = 0; bj < 2; ++bj) { const u32x4 gw = *(const u32x4*)(gp + bj * HALF);
;                     f32x4 v0 = acc[ai][bj][m][0], v1 = acc[ai][bj][m][1];
;                     v0[0] *= bf_lo(gw.x); v0[1] *= bf_hi(gw.x); v0[2] *= bf_lo(gw.y); v0[3] *= bf_hi(gw.y);
;                     v1[0] *= bf_lo(gw.z); v1[1] *= bf_hi(gw.z); v1[2] *= bf_lo(gw.w); v1[3] *= bf_hi(gw.w);
;                     if (ACCUM) { const u32x4 pw = *(const u32x4*)(rowp + bj * HALF);
;                         v0[0] += bf_lo(pw.x); v0[1] += bf_hi(pw.x); v0[2] += bf_lo(pw.y); v0[3] += bf_hi(pw.y);
;                         v1[0] += bf_lo(pw.z); v1[1] += bf_hi(pw.z); v1[2] += bf_lo(pw.w); v1[3] += bf_hi(pw.w); }
;                     u32x4 w; w.x = cvt_pk_bf16(v0[0], v0[1]); w.y = cvt_pk_bf16(v0[2], v0[3]); w.z = cvt_pk_bf16(v1[0], v1[1]); w.w = cvt_pk_bf16(v1[2], v1[3]);
;                     *(u32x4*)(rowp + bj * HALF) = w; } }
; template <class Epi, class Sched>
; __device__ __forceinline__ void gemm_phase(PG8_LAS unsigned char* lds, const Gemm g, const Sched& S, const Epi& E) {
;     ...
;             PG8_WAIT_V(6); PG8_BAR; PG8_MMA(1, 1, At, B1); PG8_BAR;
;         }
	s_add_i32 s47, s47, 2
	s_add_u32 s18, s18, 0x100
	s_addc_u32 s19, s19, 0
	s_add_u32 s45, s45, 0x100
	s_addc_u32 s46, s46, 0
	s_cmp_gt_u32 s47, 13
	s_cbranch_scc0 .LBB0_1011
	v_lshl_add_u32 v146, s16, 8, v150
	v_lshl_or_b32 v144, s42, 8, v152
	v_ashrrev_i32_e32 v147, 31, v146
	v_ashrrev_i32_e32 v145, 31, v144
	v_mov_b64_e32 v[148:149], s[4:5]
	v_lshlrev_b64 v[160:161], 11, v[146:147]
	v_lshlrev_b64 v[144:145], 1, v[144:145]
	v_mad_i64_i32 v[156:157], s[18:19], v146, s41, v[148:149]
	v_lshl_add_u64 v[160:161], s[0:1], 0, v[160:161]
	v_lshl_add_u64 v[164:165], v[156:157], 0, v[144:145]
	v_lshl_add_u64 v[166:167], v[160:161], 0, v[144:145]
	v_mov_b64_e32 v[218:219], v[164:165]
	v_mov_b64_e32 v[220:221], v[166:167]
	s_mul_i32 s98, s41, 0
	s_mov_b32 s99, 0
	v_lshl_add_u64 v[222:223], v[218:219], 0, s[98:99]
	global_load_dwordx4 v[182:185], v[222:223], off
	s_mov_b32 s98, 0
	v_lshl_add_u64 v[224:225], v[220:221], 0, s[98:99]
	global_load_dwordx4 v[190:193], v[224:225], off
	s_mul_i32 s98, s41, 0
	s_mov_b32 s99, 0
	v_lshl_add_u64 v[222:223], v[218:219], 0, s[98:99]
	global_load_dwordx4 v[194:197], v[222:223], off offset:256
	s_mov_b32 s98, 0
	v_lshl_add_u64 v[224:225], v[220:221], 0, s[98:99]
	global_load_dwordx4 v[198:201], v[224:225], off offset:256
	s_mul_i32 s98, s41, 16
	s_mov_b32 s99, 0
	v_lshl_add_u64 v[222:223], v[218:219], 0, s[98:99]
	global_load_dwordx4 v[202:205], v[222:223], off
	s_mov_b32 s98, 32768
	v_lshl_add_u64 v[224:225], v[220:221], 0, s[98:99]
	global_load_dwordx4 v[206:209], v[224:225], off
	s_mul_i32 s98, s41, 16
	s_mov_b32 s99, 0
	v_lshl_add_u64 v[222:223], v[218:219], 0, s[98:99]
	global_load_dwordx4 v[210:213], v[222:223], off offset:256
	s_mov_b32 s98, 32768
	v_lshl_add_u64 v[224:225], v[220:221], 0, s[98:99]
	global_load_dwordx4 v[214:217], v[224:225], off offset:256
	s_and_b64 vcc, exec, s[2:3]
	s_mov_b32 s42, s8
	s_mov_b32 s16, s10
	s_mov_b64 s[20:21], s[14:15]
	s_waitcnt vmcnt(6)
	v_mov_b32_e32 v156, v182
	v_mov_b32_e32 v157, v183
	v_mov_b32_e32 v158, v184
	v_mov_b32_e32 v159, v185
	v_mov_b32_e32 v160, v190
	v_mov_b32_e32 v161, v191
	v_mov_b32_e32 v162, v192
	v_mov_b32_e32 v163, v193
	s_mul_i32 s98, s41, 32
	s_mov_b32 s99, 0
	v_lshl_add_u64 v[222:223], v[218:219], 0, s[98:99]
	global_load_dwordx4 v[182:185], v[222:223], off
	s_mov_b32 s98, 65536
	v_lshl_add_u64 v[224:225], v[220:221], 0, s[98:99]
	global_load_dwordx4 v[190:193], v[224:225], off
	v_lshlrev_b32_e32 v147, 16, v156
	v_and_b32_e32 v156, 0xffff0000, v156
	v_lshlrev_b32_e32 v168, 16, v157
	v_and_b32_e32 v157, 0xffff0000, v157
	v_lshlrev_b32_e32 v169, 16, v158
	v_and_b32_e32 v158, 0xffff0000, v158
	v_lshlrev_b32_e32 v170, 16, v159
	v_and_b32_e32 v159, 0xffff0000, v159
	v_lshlrev_b32_e32 v171, 16, v160
	v_and_b32_e32 v160, 0xffff0000, v160
	v_lshlrev_b32_e32 v172, 16, v161
	v_and_b32_e32 v161, 0xffff0000, v161
	v_lshlrev_b32_e32 v173, 16, v162
	v_and_b32_e32 v162, 0xffff0000, v162
	v_lshlrev_b32_e32 v174, 16, v163
	v_and_b32_e32 v163, 0xffff0000, v163
	v_fmac_f32_e32 v171, v124, v147
	v_fmac_f32_e32 v160, v125, v156
	v_fmac_f32_e32 v172, v126, v168
	v_fmac_f32_e32 v161, v127, v157
	v_fmac_f32_e32 v173, v120, v169
	v_fmac_f32_e32 v162, v121, v158
	v_fmac_f32_e32 v174, v122, v170
	v_fmac_f32_e32 v163, v123, v159
	v_cvt_pk_bf16_f32 v120, v171, v160
	v_cvt_pk_bf16_f32 v121, v172, v161
	v_cvt_pk_bf16_f32 v122, v173, v162
	v_cvt_pk_bf16_f32 v123, v174, v163
	v_or_b32_e32 v160, 16, v146
	global_store_dwordx4 v[166:167], v[120:123], off
	v_mad_i64_i32 v[162:163], s[18:19], v160, s41, v[148:149]
	v_lshl_add_u64 v[162:163], v[162:163], 0, v[144:145]
	s_waitcnt vmcnt(7)
	v_mov_b32_e32 v124, v194
	v_mov_b32_e32 v125, v195
	v_mov_b32_e32 v126, v196
	v_mov_b32_e32 v127, v197
	v_mov_b32_e32 v156, v198
	v_mov_b32_e32 v157, v199
	v_mov_b32_e32 v158, v200
	v_mov_b32_e32 v159, v201
	s_mul_i32 s98, s41, 32
	s_mov_b32 s99, 0
	v_lshl_add_u64 v[222:223], v[218:219], 0, s[98:99]
	global_load_dwordx4 v[194:197], v[222:223], off offset:256
	s_mov_b32 s98, 65536
	v_lshl_add_u64 v[224:225], v[220:221], 0, s[98:99]
	global_load_dwordx4 v[198:201], v[224:225], off offset:256
	v_lshlrev_b32_e32 v122, 16, v125
	v_lshlrev_b32_e32 v161, 16, v157
	v_lshlrev_b32_e32 v120, 16, v124
	v_and_b32_e32 v121, 0xffff0000, v124
	v_and_b32_e32 v123, 0xffff0000, v125
	v_lshlrev_b32_e32 v124, 16, v126
	v_and_b32_e32 v125, 0xffff0000, v126
	v_lshlrev_b32_e32 v147, 16, v156
	v_and_b32_e32 v156, 0xffff0000, v156
	v_and_b32_e32 v157, 0xffff0000, v157
	v_lshlrev_b32_e32 v164, 16, v158
	v_and_b32_e32 v158, 0xffff0000, v158
	v_fmac_f32_e32 v161, v118, v122
	v_fmac_f32_e32 v147, v116, v120
	v_fmac_f32_e32 v156, v117, v121
	v_fmac_f32_e32 v157, v119, v123
	v_fmac_f32_e32 v164, v112, v124
	v_fmac_f32_e32 v158, v113, v125
	v_cvt_pk_bf16_f32 v112, v147, v156
	v_cvt_pk_bf16_f32 v113, v161, v157
	v_ashrrev_i32_e32 v161, 31, v160
	v_lshlrev_b64 v[120:121], 11, v[160:161]
	v_lshl_add_u64 v[120:121], s[0:1], 0, v[120:121]
	v_lshlrev_b32_e32 v126, 16, v127
	v_and_b32_e32 v127, 0xffff0000, v127
	v_lshlrev_b32_e32 v165, 16, v159
	v_and_b32_e32 v159, 0xffff0000, v159
	v_lshl_add_u64 v[124:125], v[120:121], 0, v[144:145]
	v_fmac_f32_e32 v165, v114, v126
	v_fmac_f32_e32 v159, v115, v127
	v_cvt_pk_bf16_f32 v114, v164, v158
	v_cvt_pk_bf16_f32 v115, v165, v159
	s_waitcnt vmcnt(7)
; __device__ __forceinline__ unsigned cvt_pk_bf16(float lo, float hi) { unsigned r; asm volatile("v_cvt_pk_bf16_f32 %0, %1, %2" : "=v"(r) : "v"(lo), "v"(hi)); return r; }
; __device__ __forceinline__ float bf_lo(unsigned u) { return __uint_as_float(u << 16); }
; __device__ __forceinline__ float bf_hi(unsigned u) { return __uint_as_float(u & 0xffff0000u); }
;     __device__ __forceinline__ void operator()(const f32x4 (&acc)[2][2][4][2], const Unit& u, int wr, int wc, int fr, int fq) const {
;     ...
;             for (int m = 0; m < 4; ++m) { const size_t r = (size_t)(row0 + ai * HALF + m * 16); bf16_t* rowp = O + r * ldc + col0; const bf16_t* gp = G + r * ldg + col0;
; #pragma unroll
;                 for (int bj = 0; bj < 2; ++bj) { const u32x4 gw = *(const u32x4*)(gp + bj * HALF);
;                     f32x4 v0 = acc[ai][bj][m][0], v1 = acc[ai][bj][m][1];
;                     v0[0] *= bf_lo(gw.x); v0[1] *= bf_hi(gw.x); v0[2] *= bf_lo(gw.y); v0[3] *= bf_hi(gw.y);
;                     v1[0] *= bf_lo(gw.z); v1[1] *= bf_hi(gw.z); v1[2] *= bf_lo(gw.w); v1[3] *= bf_hi(gw.w);
;                     if (ACCUM) { const u32x4 pw = *(const u32x4*)(rowp + bj * HALF);
;                         v0[0] += bf_lo(pw.x); v0[1] += bf_hi(pw.x); v0[2] += bf_lo(pw.y); v0[3] += bf_hi(pw.y);
;                         v1[0] += bf_lo(pw.z); v1[1] += bf_hi(pw.z); v1[2] += bf_lo(pw.w); v1[3] += bf_hi(pw.w); }
;                     u32x4 w; w.x = cvt_pk_bf16(v0[0], v0[1]); w.y = cvt_pk_bf16(v0[2], v0[3]); w.z = cvt_pk_bf16(v1[0], v1[1]); w.w = cvt_pk_bf16(v1[2], v1[3]);
;                     *(u32x4*)(rowp + bj * HALF) = w; } }
	v_mov_b32_e32 v116, v202
	v_mov_b32_e32 v117, v203
	v_mov_b32_e32 v118, v204
	v_mov_b32_e32 v119, v205
	v_mov_b32_e32 v120, v206
	v_mov_b32_e32 v121, v207
	v_mov_b32_e32 v122, v208
	v_mov_b32_e32 v123, v209
	s_mul_i32 s98, s41, 48
	s_mov_b32 s99, 0
	v_lshl_add_u64 v[222:223], v[218:219], 0, s[98:99]
	global_load_dwordx4 v[202:205], v[222:223], off
	s_mov_b32 s98, 98304
	v_lshl_add_u64 v[224:225], v[220:221], 0, s[98:99]
	global_load_dwordx4 v[206:209], v[224:225], off
	v_lshlrev_b32_e32 v126, 16, v120
	global_store_dwordx4 v[166:167], v[112:115], off offset:256
	v_and_b32_e32 v120, 0xffff0000, v120
	v_lshlrev_b32_e32 v127, 16, v121
	v_lshlrev_b32_e32 v112, 16, v116
	v_and_b32_e32 v113, 0xffff0000, v116
	v_lshlrev_b32_e32 v114, 16, v117
	v_and_b32_e32 v115, 0xffff0000, v117
	v_lshlrev_b32_e32 v116, 16, v118
	v_and_b32_e32 v117, 0xffff0000, v118
	v_lshlrev_b32_e32 v118, 16, v119
	v_and_b32_e32 v119, 0xffff0000, v119
	v_and_b32_e32 v121, 0xffff0000, v121
	v_lshlrev_b32_e32 v147, 16, v122
	v_and_b32_e32 v122, 0xffff0000, v122
	v_lshlrev_b32_e32 v156, 16, v123
	v_and_b32_e32 v123, 0xffff0000, v123
	v_fmac_f32_e32 v126, v108, v112
	v_fmac_f32_e32 v120, v109, v113
	v_fmac_f32_e32 v127, v110, v114
	v_fmac_f32_e32 v121, v111, v115
	v_fmac_f32_e32 v147, v104, v116
	v_fmac_f32_e32 v122, v105, v117
	v_fmac_f32_e32 v156, v106, v118
	v_fmac_f32_e32 v123, v107, v119
	v_cvt_pk_bf16_f32 v104, v126, v120
	v_cvt_pk_bf16_f32 v105, v127, v121
	v_cvt_pk_bf16_f32 v106, v147, v122
	v_cvt_pk_bf16_f32 v107, v156, v123
	v_or_b32_e32 v116, 32, v146
	global_store_dwordx4 v[124:125], v[104:107], off
	v_mad_i64_i32 v[118:119], s[18:19], v116, s41, v[148:149]
	v_lshl_add_u64 v[118:119], v[118:119], 0, v[144:145]
	s_waitcnt vmcnt(9)
	v_mov_b32_e32 v108, v210
	v_mov_b32_e32 v109, v211
	v_mov_b32_e32 v110, v212
	v_mov_b32_e32 v111, v213
	v_mov_b32_e32 v112, v214
	v_mov_b32_e32 v113, v215
	v_mov_b32_e32 v114, v216
	v_mov_b32_e32 v115, v217
	s_mul_i32 s98, s41, 48
	s_mov_b32 s99, 0
	v_lshl_add_u64 v[222:223], v[218:219], 0, s[98:99]
	global_load_dwordx4 v[210:213], v[222:223], off offset:256
	s_mov_b32 s98, 98304
	v_lshl_add_u64 v[224:225], v[220:221], 0, s[98:99]
	global_load_dwordx4 v[214:217], v[224:225], off offset:256
	v_lshlrev_b32_e32 v104, 16, v108
	v_lshlrev_b32_e32 v117, 16, v112
	v_and_b32_e32 v105, 0xffff0000, v108
	v_lshlrev_b32_e32 v108, 16, v110
	v_and_b32_e32 v112, 0xffff0000, v112
	v_lshlrev_b32_e32 v121, 16, v114
	v_fmac_f32_e32 v117, v100, v104
	v_fmac_f32_e32 v112, v101, v105
	v_fmac_f32_e32 v121, v96, v108
	v_cvt_pk_bf16_f32 v96, v117, v112
	v_ashrrev_i32_e32 v117, 31, v116
	v_lshlrev_b64 v[104:105], 11, v[116:117]
	v_lshlrev_b32_e32 v106, 16, v109
	v_and_b32_e32 v107, 0xffff0000, v109
	v_and_b32_e32 v109, 0xffff0000, v110
	v_and_b32_e32 v114, 0xffff0000, v114
	v_lshl_add_u64 v[104:105], s[0:1], 0, v[104:105]
	v_lshlrev_b32_e32 v110, 16, v111
	v_and_b32_e32 v111, 0xffff0000, v111
	v_lshlrev_b32_e32 v120, 16, v113
	v_and_b32_e32 v113, 0xffff0000, v113
	v_lshlrev_b32_e32 v122, 16, v115
	v_and_b32_e32 v115, 0xffff0000, v115
	v_fmac_f32_e32 v114, v97, v109
	v_lshl_add_u64 v[108:109], v[104:105], 0, v[144:145]
	v_fmac_f32_e32 v120, v102, v106
	v_fmac_f32_e32 v113, v103, v107
	v_fmac_f32_e32 v122, v98, v110
	v_fmac_f32_e32 v115, v99, v111
	v_cvt_pk_bf16_f32 v97, v120, v113
	v_cvt_pk_bf16_f32 v98, v121, v114
	v_cvt_pk_bf16_f32 v99, v122, v115
	s_waitcnt vmcnt(9)
	v_mov_b32_e32 v100, v182
	v_mov_b32_e32 v101, v183
	v_mov_b32_e32 v102, v184
	v_mov_b32_e32 v103, v185
	v_mov_b32_e32 v104, v190
	v_mov_b32_e32 v105, v191
	v_mov_b32_e32 v106, v192
	v_mov_b32_e32 v107, v193
	s_mul_i32 s98, s41, 128
	s_mov_b32 s99, 0
	v_lshl_add_u64 v[222:223], v[218:219], 0, s[98:99]
	global_load_dwordx4 v[182:185], v[222:223], off
	s_mov_b32 s98, 262144
	v_lshl_add_u64 v[224:225], v[220:221], 0, s[98:99]
	global_load_dwordx4 v[190:193], v[224:225], off
	v_lshlrev_b32_e32 v110, 16, v104
	global_store_dwordx4 v[124:125], v[96:99], off offset:256
	v_and_b32_e32 v104, 0xffff0000, v104
	v_lshlrev_b32_e32 v111, 16, v105
	v_lshlrev_b32_e32 v96, 16, v100
	v_and_b32_e32 v97, 0xffff0000, v100
	v_lshlrev_b32_e32 v98, 16, v101
	v_and_b32_e32 v99, 0xffff0000, v101
	v_lshlrev_b32_e32 v100, 16, v102
	v_and_b32_e32 v101, 0xffff0000, v102
	v_lshlrev_b32_e32 v102, 16, v103
	v_and_b32_e32 v103, 0xffff0000, v103
	v_and_b32_e32 v105, 0xffff0000, v105
	v_lshlrev_b32_e32 v112, 16, v106
	v_and_b32_e32 v106, 0xffff0000, v106
	v_lshlrev_b32_e32 v113, 16, v107
	v_and_b32_e32 v107, 0xffff0000, v107
	v_fmac_f32_e32 v110, v92, v96
	v_fmac_f32_e32 v104, v93, v97
	v_fmac_f32_e32 v111, v94, v98
	v_fmac_f32_e32 v105, v95, v99
	v_fmac_f32_e32 v112, v88, v100
	v_fmac_f32_e32 v106, v89, v101
	v_fmac_f32_e32 v113, v90, v102
	v_fmac_f32_e32 v107, v91, v103
	v_cvt_pk_bf16_f32 v88, v110, v104
	v_cvt_pk_bf16_f32 v89, v111, v105
	v_cvt_pk_bf16_f32 v90, v112, v106
	v_cvt_pk_bf16_f32 v91, v113, v107
	v_or_b32_e32 v100, 48, v146
	global_store_dwordx4 v[108:109], v[88:91], off
	v_mad_i64_i32 v[102:103], s[18:19], v100, s41, v[148:149]
	v_lshl_add_u64 v[102:103], v[102:103], 0, v[144:145]
	s_waitcnt vmcnt(10)
; __device__ __forceinline__ unsigned cvt_pk_bf16(float lo, float hi) { unsigned r; asm volatile("v_cvt_pk_bf16_f32 %0, %1, %2" : "=v"(r) : "v"(lo), "v"(hi)); return r; }
; __device__ __forceinline__ float bf_lo(unsigned u) { return __uint_as_float(u << 16); }
; __device__ __forceinline__ float bf_hi(unsigned u) { return __uint_as_float(u & 0xffff0000u); }
;     __device__ __forceinline__ void operator()(const f32x4 (&acc)[2][2][4][2], const Unit& u, int wr, int wc, int fr, int fq) const {
;     ...
;             for (int m = 0; m < 4; ++m) { const size_t r = (size_t)(row0 + ai * HALF + m * 16); bf16_t* rowp = O + r * ldc + col0; const bf16_t* gp = G + r * ldg + col0;
; #pragma unroll
;                 for (int bj = 0; bj < 2; ++bj) { const u32x4 gw = *(const u32x4*)(gp + bj * HALF);
;                     f32x4 v0 = acc[ai][bj][m][0], v1 = acc[ai][bj][m][1];
;                     v0[0] *= bf_lo(gw.x); v0[1] *= bf_hi(gw.x); v0[2] *= bf_lo(gw.y); v0[3] *= bf_hi(gw.y);
;                     v1[0] *= bf_lo(gw.z); v1[1] *= bf_hi(gw.z); v1[2] *= bf_lo(gw.w); v1[3] *= bf_hi(gw.w);
;                     if (ACCUM) { const u32x4 pw = *(const u32x4*)(rowp + bj * HALF);
;                         v0[0] += bf_lo(pw.x); v0[1] += bf_hi(pw.x); v0[2] += bf_lo(pw.y); v0[3] += bf_hi(pw.y);
;                         v1[0] += bf_lo(pw.z); v1[1] += bf_hi(pw.z); v1[2] += bf_lo(pw.w); v1[3] += bf_hi(pw.w); }
;                     u32x4 w; w.x = cvt_pk_bf16(v0[0], v0[1]); w.y = cvt_pk_bf16(v0[2], v0[3]); w.z = cvt_pk_bf16(v1[0], v1[1]); w.w = cvt_pk_bf16(v1[2], v1[3]);
;                     *(u32x4*)(rowp + bj * HALF) = w; } }
	v_mov_b32_e32 v92, v194
	v_mov_b32_e32 v93, v195
	v_mov_b32_e32 v94, v196
	v_mov_b32_e32 v95, v197
	v_mov_b32_e32 v96, v198
	v_mov_b32_e32 v97, v199
	v_mov_b32_e32 v98, v200
	v_mov_b32_e32 v99, v201
	s_mul_i32 s98, s41, 128
	s_mov_b32 s99, 0
	v_lshl_add_u64 v[222:223], v[218:219], 0, s[98:99]
	global_load_dwordx4 v[194:197], v[222:223], off offset:256
	s_mov_b32 s98, 262144
	v_lshl_add_u64 v[224:225], v[220:221], 0, s[98:99]
	global_load_dwordx4 v[198:201], v[224:225], off offset:256
	v_lshlrev_b32_e32 v88, 16, v92
	v_lshlrev_b32_e32 v101, 16, v96
	v_and_b32_e32 v89, 0xffff0000, v92
	v_lshlrev_b32_e32 v92, 16, v94
	v_and_b32_e32 v96, 0xffff0000, v96
	v_lshlrev_b32_e32 v105, 16, v98
	v_fmac_f32_e32 v101, v84, v88
	v_fmac_f32_e32 v96, v85, v89
	v_fmac_f32_e32 v105, v80, v92
	v_cvt_pk_bf16_f32 v80, v101, v96
	v_ashrrev_i32_e32 v101, 31, v100
	v_lshlrev_b64 v[88:89], 11, v[100:101]
	v_lshlrev_b32_e32 v90, 16, v93
	v_and_b32_e32 v91, 0xffff0000, v93
	v_and_b32_e32 v93, 0xffff0000, v94
	v_and_b32_e32 v98, 0xffff0000, v98
	v_lshl_add_u64 v[88:89], s[0:1], 0, v[88:89]
	v_lshlrev_b32_e32 v94, 16, v95
	v_and_b32_e32 v95, 0xffff0000, v95
	v_lshlrev_b32_e32 v104, 16, v97
	v_and_b32_e32 v97, 0xffff0000, v97
	v_lshlrev_b32_e32 v106, 16, v99
	v_and_b32_e32 v99, 0xffff0000, v99
	v_fmac_f32_e32 v98, v81, v93
	v_lshl_add_u64 v[92:93], v[88:89], 0, v[144:145]
	v_fmac_f32_e32 v104, v86, v90
	v_fmac_f32_e32 v97, v87, v91
	v_fmac_f32_e32 v106, v82, v94
	v_fmac_f32_e32 v99, v83, v95
	v_cvt_pk_bf16_f32 v81, v104, v97
	v_cvt_pk_bf16_f32 v82, v105, v98
	v_cvt_pk_bf16_f32 v83, v106, v99
	s_waitcnt vmcnt(10)
	v_mov_b32_e32 v84, v202
	v_mov_b32_e32 v85, v203
	v_mov_b32_e32 v86, v204
	v_mov_b32_e32 v87, v205
	v_mov_b32_e32 v88, v206
	v_mov_b32_e32 v89, v207
	v_mov_b32_e32 v90, v208
	v_mov_b32_e32 v91, v209
	s_mul_i32 s98, s41, 144
	s_mov_b32 s99, 0
	v_lshl_add_u64 v[222:223], v[218:219], 0, s[98:99]
	global_load_dwordx4 v[202:205], v[222:223], off
	s_mov_b32 s98, 294912
	v_lshl_add_u64 v[224:225], v[220:221], 0, s[98:99]
	global_load_dwordx4 v[206:209], v[224:225], off
	v_lshlrev_b32_e32 v94, 16, v88
	global_store_dwordx4 v[108:109], v[80:83], off offset:256
	v_and_b32_e32 v88, 0xffff0000, v88
	v_lshlrev_b32_e32 v95, 16, v89
	v_lshlrev_b32_e32 v80, 16, v84
	v_and_b32_e32 v81, 0xffff0000, v84
	v_lshlrev_b32_e32 v82, 16, v85
	v_and_b32_e32 v83, 0xffff0000, v85
	v_lshlrev_b32_e32 v84, 16, v86
	v_and_b32_e32 v85, 0xffff0000, v86
	v_lshlrev_b32_e32 v86, 16, v87
	v_and_b32_e32 v87, 0xffff0000, v87
	v_and_b32_e32 v89, 0xffff0000, v89
	v_lshlrev_b32_e32 v96, 16, v90
	v_and_b32_e32 v90, 0xffff0000, v90
	v_lshlrev_b32_e32 v97, 16, v91
	v_and_b32_e32 v91, 0xffff0000, v91
	v_fmac_f32_e32 v94, v76, v80
	v_fmac_f32_e32 v88, v77, v81
	v_fmac_f32_e32 v95, v78, v82
	v_fmac_f32_e32 v89, v79, v83
	v_fmac_f32_e32 v96, v72, v84
	v_fmac_f32_e32 v90, v73, v85
	v_fmac_f32_e32 v97, v74, v86
	v_fmac_f32_e32 v91, v75, v87
	v_cvt_pk_bf16_f32 v72, v94, v88
	v_cvt_pk_bf16_f32 v73, v95, v89
	v_cvt_pk_bf16_f32 v74, v96, v90
	v_cvt_pk_bf16_f32 v75, v97, v91
	v_add_u32_e32 v84, 0x80, v146
	global_store_dwordx4 v[92:93], v[72:75], off
	v_mad_i64_i32 v[86:87], s[18:19], v84, s41, v[148:149]
	v_lshl_add_u64 v[86:87], v[86:87], 0, v[144:145]
	s_waitcnt vmcnt(10)
	v_mov_b32_e32 v76, v210
	v_mov_b32_e32 v77, v211
	v_mov_b32_e32 v78, v212
	v_mov_b32_e32 v79, v213
	v_mov_b32_e32 v80, v214
	v_mov_b32_e32 v81, v215
	v_mov_b32_e32 v82, v216
	v_mov_b32_e32 v83, v217
	s_mul_i32 s98, s41, 144
	s_mov_b32 s99, 0
	v_lshl_add_u64 v[222:223], v[218:219], 0, s[98:99]
	global_load_dwordx4 v[210:213], v[222:223], off offset:256
	s_mov_b32 s98, 294912
	v_lshl_add_u64 v[224:225], v[220:221], 0, s[98:99]
	global_load_dwordx4 v[214:217], v[224:225], off offset:256
	v_lshlrev_b32_e32 v72, 16, v76
	v_lshlrev_b32_e32 v85, 16, v80
	v_and_b32_e32 v73, 0xffff0000, v76
	v_lshlrev_b32_e32 v76, 16, v78
	v_and_b32_e32 v80, 0xffff0000, v80
	v_lshlrev_b32_e32 v89, 16, v82
	v_fmac_f32_e32 v85, v68, v72
	v_fmac_f32_e32 v80, v69, v73
	v_fmac_f32_e32 v89, v64, v76
	v_cvt_pk_bf16_f32 v64, v85, v80
	v_ashrrev_i32_e32 v85, 31, v84
	v_lshlrev_b64 v[72:73], 11, v[84:85]
	v_lshlrev_b32_e32 v74, 16, v77
	v_and_b32_e32 v75, 0xffff0000, v77
	v_and_b32_e32 v77, 0xffff0000, v78
	v_and_b32_e32 v82, 0xffff0000, v82
	v_lshl_add_u64 v[72:73], s[0:1], 0, v[72:73]
	v_lshlrev_b32_e32 v78, 16, v79
	v_and_b32_e32 v79, 0xffff0000, v79
	v_lshlrev_b32_e32 v88, 16, v81
	v_and_b32_e32 v81, 0xffff0000, v81
	v_lshlrev_b32_e32 v90, 16, v83
	v_and_b32_e32 v83, 0xffff0000, v83
	v_fmac_f32_e32 v82, v65, v77
	v_lshl_add_u64 v[76:77], v[72:73], 0, v[144:145]
	v_fmac_f32_e32 v88, v70, v74
	v_fmac_f32_e32 v81, v71, v75
	v_fmac_f32_e32 v90, v66, v78
	v_fmac_f32_e32 v83, v67, v79
	v_cvt_pk_bf16_f32 v65, v88, v81
	v_cvt_pk_bf16_f32 v66, v89, v82
	v_cvt_pk_bf16_f32 v67, v90, v83
	s_waitcnt vmcnt(10)
; __device__ __forceinline__ unsigned cvt_pk_bf16(float lo, float hi) { unsigned r; asm volatile("v_cvt_pk_bf16_f32 %0, %1, %2" : "=v"(r) : "v"(lo), "v"(hi)); return r; }
; __device__ __forceinline__ float bf_lo(unsigned u) { return __uint_as_float(u << 16); }
; __device__ __forceinline__ float bf_hi(unsigned u) { return __uint_as_float(u & 0xffff0000u); }
;     __device__ __forceinline__ void operator()(const f32x4 (&acc)[2][2][4][2], const Unit& u, int wr, int wc, int fr, int fq) const {
;     ...
;             for (int m = 0; m < 4; ++m) { const size_t r = (size_t)(row0 + ai * HALF + m * 16); bf16_t* rowp = O + r * ldc + col0; const bf16_t* gp = G + r * ldg + col0;
; #pragma unroll
;                 for (int bj = 0; bj < 2; ++bj) { const u32x4 gw = *(const u32x4*)(gp + bj * HALF);
;                     f32x4 v0 = acc[ai][bj][m][0], v1 = acc[ai][bj][m][1];
;                     v0[0] *= bf_lo(gw.x); v0[1] *= bf_hi(gw.x); v0[2] *= bf_lo(gw.y); v0[3] *= bf_hi(gw.y);
;                     v1[0] *= bf_lo(gw.z); v1[1] *= bf_hi(gw.z); v1[2] *= bf_lo(gw.w); v1[3] *= bf_hi(gw.w);
;                     if (ACCUM) { const u32x4 pw = *(const u32x4*)(rowp + bj * HALF);
;                         v0[0] += bf_lo(pw.x); v0[1] += bf_hi(pw.x); v0[2] += bf_lo(pw.y); v0[3] += bf_hi(pw.y);
;                         v1[0] += bf_lo(pw.z); v1[1] += bf_hi(pw.z); v1[2] += bf_lo(pw.w); v1[3] += bf_hi(pw.w); }
;                     u32x4 w; w.x = cvt_pk_bf16(v0[0], v0[1]); w.y = cvt_pk_bf16(v0[2], v0[3]); w.z = cvt_pk_bf16(v1[0], v1[1]); w.w = cvt_pk_bf16(v1[2], v1[3]);
;                     *(u32x4*)(rowp + bj * HALF) = w; } }
	v_mov_b32_e32 v68, v182
	v_mov_b32_e32 v69, v183
	v_mov_b32_e32 v70, v184
	v_mov_b32_e32 v71, v185
	v_mov_b32_e32 v72, v190
	v_mov_b32_e32 v73, v191
	v_mov_b32_e32 v74, v192
	v_mov_b32_e32 v75, v193
	s_mul_i32 s98, s41, 160
	s_mov_b32 s99, 0
	v_lshl_add_u64 v[222:223], v[218:219], 0, s[98:99]
	global_load_dwordx4 v[182:185], v[222:223], off
	s_mov_b32 s98, 327680
	v_lshl_add_u64 v[224:225], v[220:221], 0, s[98:99]
	global_load_dwordx4 v[190:193], v[224:225], off
	v_lshlrev_b32_e32 v78, 16, v72
	global_store_dwordx4 v[92:93], v[64:67], off offset:256
	v_and_b32_e32 v72, 0xffff0000, v72
	v_lshlrev_b32_e32 v79, 16, v73
	v_lshlrev_b32_e32 v64, 16, v68
	v_and_b32_e32 v65, 0xffff0000, v68
	v_lshlrev_b32_e32 v66, 16, v69
	v_and_b32_e32 v67, 0xffff0000, v69
	v_lshlrev_b32_e32 v68, 16, v70
	v_and_b32_e32 v69, 0xffff0000, v70
	v_lshlrev_b32_e32 v70, 16, v71
	v_and_b32_e32 v71, 0xffff0000, v71
	v_and_b32_e32 v73, 0xffff0000, v73
	v_lshlrev_b32_e32 v80, 16, v74
	v_and_b32_e32 v74, 0xffff0000, v74
	v_lshlrev_b32_e32 v81, 16, v75
	v_and_b32_e32 v75, 0xffff0000, v75
	v_fmac_f32_e32 v78, v60, v64
	v_fmac_f32_e32 v72, v61, v65
	v_fmac_f32_e32 v79, v62, v66
	v_fmac_f32_e32 v73, v63, v67
	v_fmac_f32_e32 v80, v56, v68
	v_fmac_f32_e32 v74, v57, v69
	v_fmac_f32_e32 v81, v58, v70
	v_fmac_f32_e32 v75, v59, v71
	v_cvt_pk_bf16_f32 v56, v78, v72
	v_cvt_pk_bf16_f32 v57, v79, v73
	v_cvt_pk_bf16_f32 v58, v80, v74
	v_cvt_pk_bf16_f32 v59, v81, v75
	v_add_u32_e32 v68, 0x90, v146
	global_store_dwordx4 v[76:77], v[56:59], off
	v_mad_i64_i32 v[70:71], s[18:19], v68, s41, v[148:149]
	v_lshl_add_u64 v[70:71], v[70:71], 0, v[144:145]
	s_waitcnt vmcnt(10)
	v_mov_b32_e32 v60, v194
	v_mov_b32_e32 v61, v195
	v_mov_b32_e32 v62, v196
	v_mov_b32_e32 v63, v197
	v_mov_b32_e32 v64, v198
	v_mov_b32_e32 v65, v199
	v_mov_b32_e32 v66, v200
	v_mov_b32_e32 v67, v201
	s_mul_i32 s98, s41, 160
	s_mov_b32 s99, 0
	v_lshl_add_u64 v[222:223], v[218:219], 0, s[98:99]
	global_load_dwordx4 v[194:197], v[222:223], off offset:256
	s_mov_b32 s98, 327680
	v_lshl_add_u64 v[224:225], v[220:221], 0, s[98:99]
	global_load_dwordx4 v[198:201], v[224:225], off offset:256
	v_lshlrev_b32_e32 v56, 16, v60
	v_lshlrev_b32_e32 v69, 16, v64
	v_and_b32_e32 v57, 0xffff0000, v60
	v_lshlrev_b32_e32 v60, 16, v62
	v_and_b32_e32 v64, 0xffff0000, v64
	v_lshlrev_b32_e32 v73, 16, v66
	v_fmac_f32_e32 v69, v52, v56
	v_fmac_f32_e32 v64, v53, v57
	v_fmac_f32_e32 v73, v48, v60
	v_cvt_pk_bf16_f32 v48, v69, v64
	v_ashrrev_i32_e32 v69, 31, v68
	v_lshlrev_b64 v[56:57], 11, v[68:69]
	v_lshlrev_b32_e32 v58, 16, v61
	v_and_b32_e32 v59, 0xffff0000, v61
	v_and_b32_e32 v61, 0xffff0000, v62
	v_and_b32_e32 v66, 0xffff0000, v66
	v_lshl_add_u64 v[56:57], s[0:1], 0, v[56:57]
	v_lshlrev_b32_e32 v62, 16, v63
	v_and_b32_e32 v63, 0xffff0000, v63
	v_lshlrev_b32_e32 v72, 16, v65
	v_and_b32_e32 v65, 0xffff0000, v65
	v_lshlrev_b32_e32 v74, 16, v67
	v_and_b32_e32 v67, 0xffff0000, v67
	v_fmac_f32_e32 v66, v49, v61
	v_lshl_add_u64 v[60:61], v[56:57], 0, v[144:145]
	v_fmac_f32_e32 v72, v54, v58
	v_fmac_f32_e32 v65, v55, v59
	v_fmac_f32_e32 v74, v50, v62
	v_fmac_f32_e32 v67, v51, v63
	v_cvt_pk_bf16_f32 v49, v72, v65
	v_cvt_pk_bf16_f32 v50, v73, v66
	v_cvt_pk_bf16_f32 v51, v74, v67
	s_waitcnt vmcnt(10)
	v_mov_b32_e32 v52, v202
	v_mov_b32_e32 v53, v203
	v_mov_b32_e32 v54, v204
	v_mov_b32_e32 v55, v205
	v_mov_b32_e32 v56, v206
	v_mov_b32_e32 v57, v207
	v_mov_b32_e32 v58, v208
	v_mov_b32_e32 v59, v209
	s_mul_i32 s98, s41, 176
	s_mov_b32 s99, 0
	v_lshl_add_u64 v[222:223], v[218:219], 0, s[98:99]
	global_load_dwordx4 v[202:205], v[222:223], off
	s_mov_b32 s98, 360448
	v_lshl_add_u64 v[224:225], v[220:221], 0, s[98:99]
	global_load_dwordx4 v[206:209], v[224:225], off
	v_lshlrev_b32_e32 v62, 16, v56
	global_store_dwordx4 v[76:77], v[48:51], off offset:256
	v_and_b32_e32 v56, 0xffff0000, v56
	v_lshlrev_b32_e32 v63, 16, v57
	v_lshlrev_b32_e32 v48, 16, v52
	v_and_b32_e32 v49, 0xffff0000, v52
	v_lshlrev_b32_e32 v50, 16, v53
	v_and_b32_e32 v51, 0xffff0000, v53
	v_lshlrev_b32_e32 v52, 16, v54
	v_and_b32_e32 v53, 0xffff0000, v54
	v_lshlrev_b32_e32 v54, 16, v55
	v_and_b32_e32 v55, 0xffff0000, v55
	v_and_b32_e32 v57, 0xffff0000, v57
	v_lshlrev_b32_e32 v64, 16, v58
	v_and_b32_e32 v58, 0xffff0000, v58
	v_lshlrev_b32_e32 v65, 16, v59
	v_and_b32_e32 v59, 0xffff0000, v59
	v_fmac_f32_e32 v62, v44, v48
	v_fmac_f32_e32 v56, v45, v49
	v_fmac_f32_e32 v63, v46, v50
	v_fmac_f32_e32 v57, v47, v51
	v_fmac_f32_e32 v64, v40, v52
	v_fmac_f32_e32 v58, v41, v53
	v_fmac_f32_e32 v65, v42, v54
	v_fmac_f32_e32 v59, v43, v55
	v_cvt_pk_bf16_f32 v40, v62, v56
	v_cvt_pk_bf16_f32 v41, v63, v57
	v_cvt_pk_bf16_f32 v42, v64, v58
	v_cvt_pk_bf16_f32 v43, v65, v59
	v_add_u32_e32 v52, 0xa0, v146
	global_store_dwordx4 v[60:61], v[40:43], off
	v_mad_i64_i32 v[54:55], s[18:19], v52, s41, v[148:149]
	v_lshl_add_u64 v[54:55], v[54:55], 0, v[144:145]
	s_waitcnt vmcnt(10)
; __device__ __forceinline__ unsigned cvt_pk_bf16(float lo, float hi) { unsigned r; asm volatile("v_cvt_pk_bf16_f32 %0, %1, %2" : "=v"(r) : "v"(lo), "v"(hi)); return r; }
; __device__ __forceinline__ float bf_lo(unsigned u) { return __uint_as_float(u << 16); }
; __device__ __forceinline__ float bf_hi(unsigned u) { return __uint_as_float(u & 0xffff0000u); }
; #define PG8_WAIT_V(n) asm volatile("s_waitcnt vmcnt(" #n ")" ::: "memory")
; #define PG8_BAR __builtin_amdgcn_s_barrier()
;     __device__ __forceinline__ void operator()(const f32x4 (&acc)[2][2][4][2], const Unit& u, int wr, int wc, int fr, int fq) const {
;     ...
;             for (int m = 0; m < 4; ++m) { const size_t r = (size_t)(row0 + ai * HALF + m * 16); bf16_t* rowp = O + r * ldc + col0; const bf16_t* gp = G + r * ldg + col0;
; #pragma unroll
;                 for (int bj = 0; bj < 2; ++bj) { const u32x4 gw = *(const u32x4*)(gp + bj * HALF);
;                     f32x4 v0 = acc[ai][bj][m][0], v1 = acc[ai][bj][m][1];
;                     v0[0] *= bf_lo(gw.x); v0[1] *= bf_hi(gw.x); v0[2] *= bf_lo(gw.y); v0[3] *= bf_hi(gw.y);
;                     v1[0] *= bf_lo(gw.z); v1[1] *= bf_hi(gw.z); v1[2] *= bf_lo(gw.w); v1[3] *= bf_hi(gw.w);
;                     if (ACCUM) { const u32x4 pw = *(const u32x4*)(rowp + bj * HALF);
;                         v0[0] += bf_lo(pw.x); v0[1] += bf_hi(pw.x); v0[2] += bf_lo(pw.y); v0[3] += bf_hi(pw.y);
;                         v1[0] += bf_lo(pw.z); v1[1] += bf_hi(pw.z); v1[2] += bf_lo(pw.w); v1[3] += bf_hi(pw.w); }
;                     u32x4 w; w.x = cvt_pk_bf16(v0[0], v0[1]); w.y = cvt_pk_bf16(v0[2], v0[3]); w.z = cvt_pk_bf16(v1[0], v1[1]); w.w = cvt_pk_bf16(v1[2], v1[3]);
;                     *(u32x4*)(rowp + bj * HALF) = w; } }
; template <class Epi, class Sched>
; __device__ __forceinline__ void gemm_phase(PG8_LAS unsigned char* lds, const Gemm g, const Sched& S, const Epi& E) {
;     ...
;         if (!has_next) break;
; #pragma unroll
;         for (int a = 0; a < 2; ++a)
; #pragma unroll
;             for (int b = 0; b < 2; ++b)
; #pragma unroll
;                 for (int m = 0; m < 4; ++m)
; #pragma unroll
;                     for (int n = 0; n < 2; ++n) acc[a][b][m][n] = (f32x4){0.f, 0.f, 0.f, 0.f};
;         cur = nxt; cA = nA; cB = nB; ++ui;
;     }
;     PG8_WAIT_V(0);
;     if (wr == 0) PG8_BAR;
;     PG8_BAR;
	v_mov_b32_e32 v44, v210
	v_mov_b32_e32 v45, v211
	v_mov_b32_e32 v46, v212
	v_mov_b32_e32 v47, v213
	v_mov_b32_e32 v48, v214
	v_mov_b32_e32 v49, v215
	v_mov_b32_e32 v50, v216
	v_mov_b32_e32 v51, v217
	s_mul_i32 s98, s41, 176
	s_mov_b32 s99, 0
	v_lshl_add_u64 v[222:223], v[218:219], 0, s[98:99]
	global_load_dwordx4 v[210:213], v[222:223], off offset:256
	s_mov_b32 s98, 360448
	v_lshl_add_u64 v[224:225], v[220:221], 0, s[98:99]
	global_load_dwordx4 v[214:217], v[224:225], off offset:256
	v_lshlrev_b32_e32 v40, 16, v44
	v_lshlrev_b32_e32 v53, 16, v48
	v_and_b32_e32 v41, 0xffff0000, v44
	v_lshlrev_b32_e32 v44, 16, v46
	v_and_b32_e32 v48, 0xffff0000, v48
	v_lshlrev_b32_e32 v57, 16, v50
	v_fmac_f32_e32 v53, v36, v40
	v_fmac_f32_e32 v48, v37, v41
	v_fmac_f32_e32 v57, v32, v44
	v_cvt_pk_bf16_f32 v32, v53, v48
	v_ashrrev_i32_e32 v53, 31, v52
	v_lshlrev_b64 v[40:41], 11, v[52:53]
	v_lshlrev_b32_e32 v42, 16, v45
	v_and_b32_e32 v43, 0xffff0000, v45
	v_and_b32_e32 v45, 0xffff0000, v46
	v_and_b32_e32 v50, 0xffff0000, v50
	v_lshl_add_u64 v[40:41], s[0:1], 0, v[40:41]
	v_lshlrev_b32_e32 v46, 16, v47
	v_and_b32_e32 v47, 0xffff0000, v47
	v_lshlrev_b32_e32 v56, 16, v49
	v_and_b32_e32 v49, 0xffff0000, v49
	v_lshlrev_b32_e32 v58, 16, v51
	v_and_b32_e32 v51, 0xffff0000, v51
	v_fmac_f32_e32 v50, v33, v45
	v_lshl_add_u64 v[44:45], v[40:41], 0, v[144:145]
	v_fmac_f32_e32 v56, v38, v42
	v_fmac_f32_e32 v49, v39, v43
	v_fmac_f32_e32 v58, v34, v46
	v_fmac_f32_e32 v51, v35, v47
	v_cvt_pk_bf16_f32 v33, v56, v49
	v_cvt_pk_bf16_f32 v34, v57, v50
	v_cvt_pk_bf16_f32 v35, v58, v51
	s_waitcnt vmcnt(10)
	v_mov_b32_e32 v36, v182
	v_mov_b32_e32 v37, v183
	v_mov_b32_e32 v38, v184
	v_mov_b32_e32 v39, v185
	v_mov_b32_e32 v40, v190
	v_mov_b32_e32 v41, v191
	v_mov_b32_e32 v42, v192
	v_mov_b32_e32 v43, v193
	v_lshlrev_b32_e32 v46, 16, v40
	global_store_dwordx4 v[60:61], v[32:35], off offset:256
	v_and_b32_e32 v40, 0xffff0000, v40
	v_lshlrev_b32_e32 v47, 16, v41
	v_lshlrev_b32_e32 v32, 16, v36
	v_and_b32_e32 v33, 0xffff0000, v36
	v_lshlrev_b32_e32 v34, 16, v37
	v_and_b32_e32 v35, 0xffff0000, v37
	v_lshlrev_b32_e32 v36, 16, v38
	v_and_b32_e32 v37, 0xffff0000, v38
	v_lshlrev_b32_e32 v38, 16, v39
	v_and_b32_e32 v39, 0xffff0000, v39
	v_and_b32_e32 v41, 0xffff0000, v41
	v_lshlrev_b32_e32 v48, 16, v42
	v_and_b32_e32 v42, 0xffff0000, v42
	v_lshlrev_b32_e32 v49, 16, v43
	v_and_b32_e32 v43, 0xffff0000, v43
	v_fmac_f32_e32 v46, v28, v32
	v_fmac_f32_e32 v40, v29, v33
	v_fmac_f32_e32 v47, v30, v34
	v_fmac_f32_e32 v41, v31, v35
	v_fmac_f32_e32 v48, v24, v36
	v_fmac_f32_e32 v42, v25, v37
	v_fmac_f32_e32 v49, v26, v38
	v_fmac_f32_e32 v43, v27, v39
	v_cvt_pk_bf16_f32 v24, v46, v40
	v_cvt_pk_bf16_f32 v25, v47, v41
	v_cvt_pk_bf16_f32 v26, v48, v42
	v_cvt_pk_bf16_f32 v27, v49, v43
	v_add_u32_e32 v36, 0xb0, v146
	global_store_dwordx4 v[44:45], v[24:27], off
	v_mad_i64_i32 v[38:39], s[18:19], v36, s41, v[148:149]
	v_lshl_add_u64 v[38:39], v[38:39], 0, v[144:145]
	s_mov_b64 s[18:19], s[12:13]
	s_waitcnt vmcnt(8)
	v_mov_b32_e32 v28, v194
	v_mov_b32_e32 v29, v195
	v_mov_b32_e32 v30, v196
	v_mov_b32_e32 v31, v197
	v_mov_b32_e32 v32, v198
	v_mov_b32_e32 v33, v199
	v_mov_b32_e32 v34, v200
	v_mov_b32_e32 v35, v201
	v_lshlrev_b32_e32 v24, 16, v28
	v_lshlrev_b32_e32 v37, 16, v32
	v_and_b32_e32 v25, 0xffff0000, v28
	v_lshlrev_b32_e32 v28, 16, v30
	v_and_b32_e32 v32, 0xffff0000, v32
	v_lshlrev_b32_e32 v41, 16, v34
	v_fmac_f32_e32 v37, v20, v24
	v_fmac_f32_e32 v32, v21, v25
	v_fmac_f32_e32 v41, v16, v28
	v_cvt_pk_bf16_f32 v16, v37, v32
	v_ashrrev_i32_e32 v37, 31, v36
	v_lshlrev_b64 v[24:25], 11, v[36:37]
	v_lshlrev_b32_e32 v26, 16, v29
	v_and_b32_e32 v27, 0xffff0000, v29
	v_and_b32_e32 v29, 0xffff0000, v30
	v_and_b32_e32 v34, 0xffff0000, v34
	v_lshl_add_u64 v[24:25], s[0:1], 0, v[24:25]
	v_lshlrev_b32_e32 v30, 16, v31
	v_and_b32_e32 v31, 0xffff0000, v31
	v_lshlrev_b32_e32 v40, 16, v33
	v_and_b32_e32 v33, 0xffff0000, v33
	v_lshlrev_b32_e32 v42, 16, v35
	v_and_b32_e32 v35, 0xffff0000, v35
	v_fmac_f32_e32 v34, v17, v29
	v_lshl_add_u64 v[28:29], v[24:25], 0, v[144:145]
	v_fmac_f32_e32 v40, v22, v26
	v_fmac_f32_e32 v33, v23, v27
	v_fmac_f32_e32 v42, v18, v30
	v_fmac_f32_e32 v35, v19, v31
	v_cvt_pk_bf16_f32 v17, v40, v33
	v_cvt_pk_bf16_f32 v18, v41, v34
	v_cvt_pk_bf16_f32 v19, v42, v35
	s_waitcnt vmcnt(6)
	v_mov_b32_e32 v20, v202
	v_mov_b32_e32 v21, v203
	v_mov_b32_e32 v22, v204
	v_mov_b32_e32 v23, v205
	v_mov_b32_e32 v24, v206
	v_mov_b32_e32 v25, v207
	v_mov_b32_e32 v26, v208
	v_mov_b32_e32 v27, v209
	v_lshlrev_b32_e32 v30, 16, v24
	global_store_dwordx4 v[44:45], v[16:19], off offset:256
	v_and_b32_e32 v24, 0xffff0000, v24
	v_lshlrev_b32_e32 v31, 16, v25
	v_lshlrev_b32_e32 v16, 16, v20
	v_and_b32_e32 v17, 0xffff0000, v20
	v_lshlrev_b32_e32 v18, 16, v21
	v_and_b32_e32 v19, 0xffff0000, v21
	v_lshlrev_b32_e32 v20, 16, v22
	v_and_b32_e32 v21, 0xffff0000, v22
	v_lshlrev_b32_e32 v22, 16, v23
	v_and_b32_e32 v23, 0xffff0000, v23
	v_and_b32_e32 v25, 0xffff0000, v25
	v_lshlrev_b32_e32 v32, 16, v26
	v_and_b32_e32 v26, 0xffff0000, v26
	v_lshlrev_b32_e32 v33, 16, v27
	v_and_b32_e32 v27, 0xffff0000, v27
	v_fmac_f32_e32 v30, v12, v16
	v_fmac_f32_e32 v24, v13, v17
	v_fmac_f32_e32 v31, v14, v18
	v_fmac_f32_e32 v25, v15, v19
	v_fmac_f32_e32 v32, v8, v20
	v_fmac_f32_e32 v26, v9, v21
	v_fmac_f32_e32 v33, v10, v22
	v_fmac_f32_e32 v27, v11, v23
	v_cvt_pk_bf16_f32 v8, v30, v24
	v_cvt_pk_bf16_f32 v9, v31, v25
	v_cvt_pk_bf16_f32 v10, v32, v26
	v_cvt_pk_bf16_f32 v11, v33, v27
	s_waitcnt vmcnt(3)
	v_mov_b32_e32 v12, v210
	v_mov_b32_e32 v13, v211
	v_mov_b32_e32 v14, v212
	v_mov_b32_e32 v15, v213
	v_mov_b32_e32 v16, v214
	v_mov_b32_e32 v17, v215
	v_mov_b32_e32 v18, v216
	v_mov_b32_e32 v19, v217
	v_lshlrev_b32_e32 v20, 16, v16
	global_store_dwordx4 v[28:29], v[8:11], off
	v_and_b32_e32 v16, 0xffff0000, v16
	v_lshlrev_b32_e32 v21, 16, v17
	v_lshlrev_b32_e32 v8, 16, v12
	v_and_b32_e32 v9, 0xffff0000, v12
	v_lshlrev_b32_e32 v10, 16, v13
	v_and_b32_e32 v11, 0xffff0000, v13
	v_lshlrev_b32_e32 v12, 16, v14
	v_and_b32_e32 v13, 0xffff0000, v14
	v_lshlrev_b32_e32 v14, 16, v15
	v_and_b32_e32 v15, 0xffff0000, v15
	v_and_b32_e32 v17, 0xffff0000, v17
	v_lshlrev_b32_e32 v22, 16, v18
	v_and_b32_e32 v18, 0xffff0000, v18
	v_lshlrev_b32_e32 v23, 16, v19
	v_and_b32_e32 v19, 0xffff0000, v19
	v_fmac_f32_e32 v20, v4, v8
	v_fmac_f32_e32 v16, v5, v9
	v_fmac_f32_e32 v21, v6, v10
	v_fmac_f32_e32 v17, v7, v11
	v_fmac_f32_e32 v22, v0, v12
	v_fmac_f32_e32 v18, v1, v13
	v_fmac_f32_e32 v23, v2, v14
	v_fmac_f32_e32 v19, v3, v15
	v_cvt_pk_bf16_f32 v0, v20, v16
	v_cvt_pk_bf16_f32 v1, v21, v17
	v_cvt_pk_bf16_f32 v2, v22, v18
	v_cvt_pk_bf16_f32 v3, v23, v19
	global_store_dwordx4 v[28:29], v[0:3], off offset:256
	s_cbranch_vccz .LBB0_1004
	s_waitcnt vmcnt(0)
	s_cmpk_gt_u32 s25, 0xff
	s_cbranch_scc1 .LBB0_1015
	s_barrier
